# attention K loop: K fragment LDS reads 4 deep ahead of QK MFMAs, P/V fragment reads double-buffered ahead of PV MFMAs
# speedup vs baseline: 1.0134x; 1.0134x over previous
.LBB0_693:
	s_add_i32 s17, s14, s16
	s_bitcmp1_b32 s16, 0
	s_cselect_b32 s8, 0x8800, 0
	s_add_i32 s23, s8, 0
	v_add_u32_e32 v209, s23, v172
	ds_read_b128 v[234:237], v209
	v_add_u32_e32 v209, s23, v174
	ds_read_b128 v[238:241], v209
	v_add_u32_e32 v209, s23, v173
	ds_read_b128 v[242:245], v209
	v_add_u32_e32 v209, s23, v175
	ds_read_b128 v[246:249], v209
	s_and_b32 s8, s17, -5
	s_cmp_eq_u32 s8, 0
	s_waitcnt lgkmcnt(3)
	v_mfma_f32_32x32x16_bf16 v[16:31], v[234:237], v[122:125], 0
	v_add_u32_e32 v209, s23, v176
	ds_read_b128 v[234:237], v209
	s_waitcnt lgkmcnt(3)
	v_mfma_f32_32x32x16_bf16 v[16:31], v[238:241], v[126:129], v[16:31]
	v_add_u32_e32 v209, s23, v177
	ds_read_b128 v[238:241], v209
	s_waitcnt lgkmcnt(3)
	v_mfma_f32_32x32x16_bf16 v[0:15], v[242:245], v[122:125], 0
	v_add_u32_e32 v209, s23, v185
	ds_read_b128 v[242:245], v209
	s_waitcnt lgkmcnt(3)
	v_mfma_f32_32x32x16_bf16 v[0:15], v[246:249], v[126:129], v[0:15]
	v_add_u32_e32 v209, s23, v190
	ds_read_b128 v[246:249], v209
	s_waitcnt lgkmcnt(3)
	v_mfma_f32_32x32x16_bf16 v[16:31], v[234:237], v[98:101], v[16:31]
	v_add_u32_e32 v209, s23, v191
	ds_read_b128 v[234:237], v209
	s_waitcnt lgkmcnt(3)
	v_mfma_f32_32x32x16_bf16 v[0:15], v[238:241], v[98:101], v[0:15]
	v_add_u32_e32 v209, s23, v192
	ds_read_b128 v[238:241], v209
	s_waitcnt lgkmcnt(3)
	v_mfma_f32_32x32x16_bf16 v[16:31], v[242:245], v[102:105], v[16:31]
	v_add_u32_e32 v209, s23, v193
	ds_read_b128 v[242:245], v209
	s_waitcnt lgkmcnt(3)
	v_mfma_f32_32x32x16_bf16 v[0:15], v[246:249], v[102:105], v[0:15]
	v_add_u32_e32 v209, s23, v194
	ds_read_b128 v[246:249], v209
	s_waitcnt lgkmcnt(3)
	v_mfma_f32_32x32x16_bf16 v[16:31], v[234:237], v[106:109], v[16:31]
	v_add_u32_e32 v209, s23, v195
	ds_read_b128 v[234:237], v209
	s_waitcnt lgkmcnt(3)
	v_mfma_f32_32x32x16_bf16 v[0:15], v[238:241], v[106:109], v[0:15]
	v_add_u32_e32 v209, s23, v196
	ds_read_b128 v[238:241], v209
	s_waitcnt lgkmcnt(3)
	v_mfma_f32_32x32x16_bf16 v[16:31], v[242:245], v[110:113], v[16:31]
	v_add_u32_e32 v209, s23, v197
	ds_read_b128 v[242:245], v209
	s_waitcnt lgkmcnt(3)
	v_mfma_f32_32x32x16_bf16 v[0:15], v[246:249], v[110:113], v[0:15]
	v_add_u32_e32 v209, s23, v198
	ds_read_b128 v[246:249], v209
	s_waitcnt lgkmcnt(3)
	v_mfma_f32_32x32x16_bf16 v[16:31], v[234:237], v[114:117], v[16:31]
	s_waitcnt lgkmcnt(2)
	v_mfma_f32_32x32x16_bf16 v[0:15], v[238:241], v[114:117], v[0:15]
	s_waitcnt lgkmcnt(1)
	v_mfma_f32_32x32x16_bf16 v[16:31], v[242:245], v[118:121], v[16:31]
	s_waitcnt lgkmcnt(0)
	v_mfma_f32_32x32x16_bf16 v[0:15], v[246:249], v[118:121], v[0:15]
	s_nop 8
	v_sub_f32_e32 v16, v16, v206
	v_sub_f32_e32 v17, v17, v206
	v_sub_f32_e32 v18, v18, v206
	v_sub_f32_e32 v19, v19, v206
	v_sub_f32_e32 v20, v20, v206
	v_sub_f32_e32 v21, v21, v206
	v_sub_f32_e32 v22, v22, v206
	v_sub_f32_e32 v23, v23, v206
	v_sub_f32_e32 v24, v24, v206
	v_sub_f32_e32 v25, v25, v206
	v_sub_f32_e32 v26, v26, v206
	v_sub_f32_e32 v27, v27, v206
	v_sub_f32_e32 v28, v28, v206
	v_sub_f32_e32 v29, v29, v206
	v_sub_f32_e32 v30, v30, v206
	v_sub_f32_e32 v31, v31, v206
	v_sub_f32_e32 v209, v0, v206
	v_sub_f32_e32 v234, v1, v206
	v_sub_f32_e32 v235, v2, v206
	v_sub_f32_e32 v236, v3, v206
	v_sub_f32_e32 v237, v4, v206
	v_sub_f32_e32 v238, v5, v206
	v_sub_f32_e32 v239, v6, v206
	v_sub_f32_e32 v240, v7, v206
	v_sub_f32_e32 v241, v8, v206
	v_sub_f32_e32 v242, v9, v206
	v_sub_f32_e32 v243, v10, v206
	v_sub_f32_e32 v244, v11, v206
	v_sub_f32_e32 v245, v12, v206
	v_sub_f32_e32 v246, v13, v206
	v_sub_f32_e32 v247, v14, v206
	v_sub_f32_e32 v248, v15, v206
	v_exp_f32_e32 v0, v16
	v_exp_f32_e32 v1, v17
	v_exp_f32_e32 v2, v18
	v_exp_f32_e32 v3, v19
	v_exp_f32_e32 v4, v20
	v_exp_f32_e32 v5, v21
	v_exp_f32_e32 v6, v22
	v_exp_f32_e32 v7, v23
	v_exp_f32_e32 v8, v24
	v_exp_f32_e32 v9, v25
	v_exp_f32_e32 v10, v26
	v_exp_f32_e32 v11, v27
	v_exp_f32_e32 v12, v28
	v_exp_f32_e32 v13, v29
	v_exp_f32_e32 v14, v30
	v_exp_f32_e32 v15, v31
	v_exp_f32_e32 v16, v209
	v_exp_f32_e32 v17, v234
	v_exp_f32_e32 v18, v235
	v_exp_f32_e32 v19, v236
	v_exp_f32_e32 v20, v237
	v_exp_f32_e32 v21, v238
	v_exp_f32_e32 v22, v239
	v_exp_f32_e32 v23, v240
	v_exp_f32_e32 v24, v241
	v_exp_f32_e32 v25, v242
	v_exp_f32_e32 v26, v243
	v_exp_f32_e32 v27, v244
	v_exp_f32_e32 v28, v245
	v_exp_f32_e32 v29, v246
	v_exp_f32_e32 v30, v247
	v_exp_f32_e32 v31, v248
	s_cbranch_scc1 .LBB0_704
	v_add_f32_e32 v209, v208, v0
	v_add_f32_e32 v209, v1, v209
	v_add_f32_e32 v209, v2, v209
	v_add_f32_e32 v209, v3, v209
	v_add_f32_e32 v209, v4, v209
	v_add_f32_e32 v209, v5, v209
	v_add_f32_e32 v209, v6, v209
	v_add_f32_e32 v209, v7, v209
	v_add_f32_e32 v209, v8, v209
	v_add_f32_e32 v209, v9, v209
	v_add_f32_e32 v209, v10, v209
	v_add_f32_e32 v209, v11, v209
	v_add_f32_e32 v209, v12, v209
	v_add_f32_e32 v209, v13, v209
	v_add_f32_e32 v209, v14, v209
	v_add_f32_e32 v209, v15, v209
	v_add_f32_e32 v209, v16, v209
	v_add_f32_e32 v209, v17, v209
	v_add_f32_e32 v209, v18, v209
	v_add_f32_e32 v209, v19, v209
	v_add_f32_e32 v209, v20, v209
	v_add_f32_e32 v209, v21, v209
	v_add_f32_e32 v209, v22, v209
	v_add_f32_e32 v209, v23, v209
	v_add_f32_e32 v209, v24, v209
	v_add_f32_e32 v209, v25, v209
	v_add_f32_e32 v209, v26, v209
	v_add_f32_e32 v209, v27, v209
	v_add_f32_e32 v209, v28, v209
	v_add_f32_e32 v209, v29, v209
	v_add_f32_e32 v209, v30, v209
	v_add_f32_e32 v209, v31, v209
	s_cbranch_execnz .LBB0_696

.LBB0_696:
	v_cvt_pk_bf16_f32 v0, v0, v1
	v_cvt_pk_bf16_f32 v1, v2, v3
	v_cvt_pk_bf16_f32 v2, v4, v5
	v_cvt_pk_bf16_f32 v3, v6, v7
	v_cvt_pk_bf16_f32 v4, v8, v9
	v_cvt_pk_bf16_f32 v5, v10, v11
	v_cvt_pk_bf16_f32 v6, v12, v13
	v_cvt_pk_bf16_f32 v7, v14, v15
	v_cvt_pk_bf16_f32 v8, v16, v17
	v_cvt_pk_bf16_f32 v9, v18, v19
	v_cvt_pk_bf16_f32 v10, v20, v21
	v_cvt_pk_bf16_f32 v11, v22, v23
	v_cvt_pk_bf16_f32 v12, v24, v25
	v_cvt_pk_bf16_f32 v13, v26, v27
	ds_write2_b64 v204, v[0:1], v[2:3] offset1:2
	ds_write2_b64 v204, v[4:5], v[6:7] offset0:4 offset1:6
	ds_write2_b64 v204, v[8:9], v[10:11] offset0:8 offset1:10
	v_cvt_pk_bf16_f32 v0, v28, v29
	v_cvt_pk_bf16_f32 v1, v30, v31
	ds_write2_b64 v204, v[12:13], v[0:1] offset0:12 offset1:14
	s_addk_i32 s23, 0x4400
	v_add_u32_e32 v242, s23, v199
	ds_read_b128 v[0:3], v205
	ds_read_b64_tr_b16 v[16:17], v242 offset:0
	ds_read_b64_tr_b16 v[18:19], v242 offset:1088
	ds_read_b64_tr_b16 v[12:13], v242 offset:64
	ds_read_b64_tr_b16 v[14:15], v242 offset:1152
	ds_read_b64_tr_b16 v[8:9], v242 offset:128
	ds_read_b64_tr_b16 v[10:11], v242 offset:1216
	ds_read_b64_tr_b16 v[4:5], v242 offset:192
	ds_read_b64_tr_b16 v[6:7], v242 offset:1280
	v_add_u32_e32 v243, s23, v200
	ds_read_b128 v[20:23], v205 offset:32
	ds_read_b64_tr_b16 v[24:25], v243 offset:0
	ds_read_b64_tr_b16 v[26:27], v243 offset:1088
	ds_read_b64_tr_b16 v[28:29], v243 offset:64
	ds_read_b64_tr_b16 v[30:31], v243 offset:1152
	ds_read_b64_tr_b16 v[234:235], v243 offset:128
	ds_read_b64_tr_b16 v[236:237], v243 offset:1216
	ds_read_b64_tr_b16 v[238:239], v243 offset:192
	ds_read_b64_tr_b16 v[240:241], v243 offset:1280
	s_mov_b64 s[8:9], -1
	s_cmp_lt_i32 s17, s15
	s_waitcnt lgkmcnt(9)
	v_mfma_f32_32x32x16_bf16 v[82:97], v[0:3], v[16:19], v[82:97]
	v_mfma_f32_32x32x16_bf16 v[66:81], v[0:3], v[12:15], v[66:81]
	v_mfma_f32_32x32x16_bf16 v[50:65], v[0:3], v[8:11], v[50:65]
	v_mfma_f32_32x32x16_bf16 v[34:49], v[0:3], v[4:7], v[34:49]
	v_add_u32_e32 v242, s23, v201
	ds_read_b128 v[0:3], v205 offset:64
	ds_read_b64_tr_b16 v[16:17], v242 offset:0
	ds_read_b64_tr_b16 v[18:19], v242 offset:1088
	ds_read_b64_tr_b16 v[12:13], v242 offset:64
	ds_read_b64_tr_b16 v[14:15], v242 offset:1152
	ds_read_b64_tr_b16 v[8:9], v242 offset:128
	ds_read_b64_tr_b16 v[10:11], v242 offset:1216
	ds_read_b64_tr_b16 v[4:5], v242 offset:192
	ds_read_b64_tr_b16 v[6:7], v242 offset:1280
	s_waitcnt lgkmcnt(9)
	v_mfma_f32_32x32x16_bf16 v[82:97], v[20:23], v[24:27], v[82:97]
	v_mfma_f32_32x32x16_bf16 v[66:81], v[20:23], v[28:31], v[66:81]
	v_mfma_f32_32x32x16_bf16 v[50:65], v[20:23], v[234:237], v[50:65]
	v_mfma_f32_32x32x16_bf16 v[34:49], v[20:23], v[238:241], v[34:49]
	v_add_u32_e32 v243, s23, v202
	ds_read_b128 v[20:23], v205 offset:96
	ds_read_b64_tr_b16 v[24:25], v243 offset:0
	ds_read_b64_tr_b16 v[26:27], v243 offset:1088
	ds_read_b64_tr_b16 v[28:29], v243 offset:64
	ds_read_b64_tr_b16 v[30:31], v243 offset:1152
	ds_read_b64_tr_b16 v[234:235], v243 offset:128
	ds_read_b64_tr_b16 v[236:237], v243 offset:1216
	ds_read_b64_tr_b16 v[238:239], v243 offset:192
	ds_read_b64_tr_b16 v[240:241], v243 offset:1280
	s_waitcnt lgkmcnt(9)
	v_mfma_f32_32x32x16_bf16 v[82:97], v[0:3], v[16:19], v[82:97]
	v_mfma_f32_32x32x16_bf16 v[66:81], v[0:3], v[12:15], v[66:81]
	v_mfma_f32_32x32x16_bf16 v[50:65], v[0:3], v[8:11], v[50:65]
	v_mfma_f32_32x32x16_bf16 v[34:49], v[0:3], v[4:7], v[34:49]
	s_waitcnt lgkmcnt(0)
	v_mfma_f32_32x32x16_bf16 v[82:97], v[20:23], v[24:27], v[82:97]
	v_mfma_f32_32x32x16_bf16 v[66:81], v[20:23], v[28:31], v[66:81]
	v_mfma_f32_32x32x16_bf16 v[50:65], v[20:23], v[234:237], v[50:65]
	v_mfma_f32_32x32x16_bf16 v[34:49], v[20:23], v[238:241], v[34:49]
	s_cbranch_scc1 .LBB0_698
	s_add_i32 s23, s16, 1
	s_mov_b64 s[8:9], 0
